# speedup vs baseline: 1.0244x; 1.0053x over previous
; __device__ __forceinline__ ushort_t* wsb(const Params& p, size_t off) { return (ushort_t*)(p.ws + off); }
; __device__ __forceinline__ void phase_rwkv_mix(const Params& p) {
;   const float* x = p.out;
;   ushort_t* Ar = wsb(p, OFF_P + 4 * SLOT);
;   ushort_t* Ak = wsb(p, OFF_P + 5 * SLOT);
;   ushort_t* Av = wsb(p, OFF_P + 2 * SLOT);
;   ushort_t* Ag = wsb(p, OFF_P + 3 * SLOT);
;   const float* mu = p.in[I_RW_MU];
;   const long n4 = (long)T_TOK * 256;
;   for (long i = (long)blockIdx.x * 256 + threadIdx.x; i < n4; i += (long)gridDim.x * 256) {
;     const long tok = i >> 8;
;     const int c = (int)(i & 255) * 4;
;     const float4 xc = *(const float4*)(x + tok * 1024 + c);
;     float4 xp = make_float4(0.f, 0.f, 0.f, 0.f);
;     if ((tok & 4095) != 0) xp = *(const float4*)(x + (tok - 1) * 1024 + c);
;     const float dx = xp.x - xc.x, dy = xp.y - xc.y, dz = xp.z - xc.z, dw = xp.w - xc.w;
;     const float4 m0 = *(const float4*)(mu + 0 * 1024 + c), m2 = *(const float4*)(mu + 2 * 1024 + c);
;     const float4 m3 = *(const float4*)(mu + 3 * 1024 + c), m5 = *(const float4*)(mu + 5 * 1024 + c);
;     u32x2 o;
;     o.x = pack2(xc.x + dx * m0.x, xc.y + dy * m0.y); o.y = pack2(xc.z + dz * m0.z, xc.w + dw * m0.w);
;     *(u32x2*)(Ar + tok * 1024 + c) = o;
;     o.x = pack2(xc.x + dx * m2.x, xc.y + dy * m2.y); o.y = pack2(xc.z + dz * m2.z, xc.w + dw * m2.w);
;     *(u32x2*)(Ak + tok * 1024 + c) = o;
;     o.x = pack2(xc.x + dx * m3.x, xc.y + dy * m3.y); o.y = pack2(xc.z + dz * m3.z, xc.w + dw * m3.w);
;     *(u32x2*)(Av + tok * 1024 + c) = o;
;     o.x = pack2(xc.x + dx * m5.x, xc.y + dy * m5.y); o.y = pack2(xc.z + dz * m5.z, xc.w + dw * m5.w);
;     *(u32x2*)(Ag + tok * 1024 + c) = o;
;   }
.LBB0_461:
	s_or_b64 exec, exec, s[6:7]
	s_add_u32 s10, s30, 0x28000000
	s_mov_b32 s97, 0
	s_addc_u32 s11, s31, 0
	s_lshl_b64 s[0:1], s[96:97], 8
	v_lshl_add_u64 v[146:147], s[0:1], 0, v[140:141]
	s_mov_b64 s[0:1], 0x1000000
	v_cmp_gt_u64_e32 vcc, s[0:1], v[146:147]
	s_barrier
	s_and_saveexec_b64 s[6:7], vcc
	s_cbranch_execz .LBB0_466
	s_add_u32 s8, s74, 0x2000
	s_addc_u32 s9, s75, 0
	s_add_u32 s12, s74, 0x3000
	s_addc_u32 s13, s75, 0
	s_add_u32 s14, s74, 0x5000
	s_addc_u32 s15, s75, 0
	s_mov_b32 s35, s97
	s_lshl_b64 s[0:1], s[96:97], 10
	v_mov_b32_e32 v145, 0
	s_lshl_b64 s[16:17], s[34:35], 8
	v_lshl_add_u64 v[8:9], s[0:1], 0, v[144:145]
	s_lshl_b64 s[18:19], s[34:35], 10
	s_mov_b64 s[20:21], 0
	s_mov_b64 s[36:37], 0xffffff
	v_mov_b64_e32 v[10:11], v[146:147]
	s_cmp_eq_u32 s34, 0x200
	s_cbranch_scc0 .LBB0_464
	v_and_b32_e32 v32, 0x7f, v140
	v_lshrrev_b32_e32 v33, 7, v140
	s_lshl_b32 s16, s96, 7
	v_readfirstlane_b32 s0, v33
	v_lshlrev_b32_e32 v33, 4, v32
	v_lshlrev_b32_e32 v32, 5, v32
	s_lshl_b32 s0, s0, 6
	s_add_u32 s16, s16, s0
	s_lshl_b32 s17, s16, 12
	s_lshl_b32 s18, s16, 11
	s_and_b32 s19, s16, 0xfff
	v_add_u32_e32 v34, s17, v32
	v_add_u32_e32 v224, s18, v33
	v_add_u32_e32 v35, 0x1000, v34
	v_add_u32_e32 v36, 0x2000, v34
	v_add_u32_e32 v37, 0x3000, v34
	global_load_dwordx4 v[188:191], v32, s[74:75]
	global_load_dwordx4 v[192:195], v32, s[74:75] offset:16
	global_load_dwordx4 v[196:199], v32, s[8:9]
	global_load_dwordx4 v[200:203], v32, s[8:9] offset:16
	global_load_dwordx4 v[208:211], v32, s[12:13]
	global_load_dwordx4 v[212:215], v32, s[12:13] offset:16
	global_load_dwordx4 v[216:219], v32, s[14:15]
	global_load_dwordx4 v[220:223], v32, s[14:15] offset:16
	v_mov_b32_e32 v226, 0
	v_mov_b32_e32 v227, 0
	v_mov_b32_e32 v228, 0
	v_mov_b32_e32 v229, 0
	v_mov_b32_e32 v230, 0
	v_mov_b32_e32 v231, 0
	v_mov_b32_e32 v232, 0
	v_mov_b32_e32 v233, 0
	s_cmp_eq_u32 s19, 0
	s_cbranch_scc1 .Lmy_mix_go
	global_load_dwordx4 v[226:229], v34, s[28:29] offset:-4096
	global_load_dwordx4 v[230:233], v34, s[28:29] offset:-4080
.Lmy_mix_go:
	s_mov_b32 s20, 16
.Lmy_mix_loop:
	global_load_dwordx4 v[0:3], v34, s[28:29]
	global_load_dwordx4 v[4:7], v34, s[28:29] offset:16
	global_load_dwordx4 v[8:11], v35, s[28:29]
	global_load_dwordx4 v[12:15], v35, s[28:29] offset:16
	global_load_dwordx4 v[16:19], v36, s[28:29]
	global_load_dwordx4 v[20:23], v36, s[28:29] offset:16
	global_load_dwordx4 v[24:27], v37, s[28:29]
	global_load_dwordx4 v[28:31], v37, s[28:29] offset:16
	v_add_u32_e32 v34, 0x4000, v34
	v_add_u32_e32 v35, 0x4000, v35
	v_add_u32_e32 v36, 0x4000, v36
	v_add_u32_e32 v37, 0x4000, v37
	s_sub_u32 s20, s20, 1
	s_waitcnt vmcnt(6)
	v_pk_add_f32 v[234:235], v[226:227], v[0:1] neg_lo:[0,1] neg_hi:[0,1]
	v_pk_add_f32 v[236:237], v[228:229], v[2:3] neg_lo:[0,1] neg_hi:[0,1]
	v_pk_add_f32 v[238:239], v[230:231], v[4:5] neg_lo:[0,1] neg_hi:[0,1]
	v_pk_add_f32 v[240:241], v[232:233], v[6:7] neg_lo:[0,1] neg_hi:[0,1]
	v_pk_fma_f32 v[242:243], v[234:235], v[188:189], v[0:1]
	v_pk_fma_f32 v[244:245], v[236:237], v[190:191], v[2:3]
	v_pk_fma_f32 v[246:247], v[238:239], v[192:193], v[4:5]
	v_pk_fma_f32 v[248:249], v[240:241], v[194:195], v[6:7]
	v_cvt_pk_bf16_f32 v250, v242, v243
	v_cvt_pk_bf16_f32 v251, v244, v245
	v_cvt_pk_bf16_f32 v252, v246, v247
	v_cvt_pk_bf16_f32 v253, v248, v249
	global_store_dwordx4 v224, v[250:253], s[42:43]
	v_pk_fma_f32 v[242:243], v[234:235], v[196:197], v[0:1]
	v_pk_fma_f32 v[244:245], v[236:237], v[198:199], v[2:3]
	v_pk_fma_f32 v[246:247], v[238:239], v[200:201], v[4:5]
	v_pk_fma_f32 v[248:249], v[240:241], v[202:203], v[6:7]
	v_cvt_pk_bf16_f32 v250, v242, v243
	v_cvt_pk_bf16_f32 v251, v244, v245
	v_cvt_pk_bf16_f32 v252, v246, v247
	v_cvt_pk_bf16_f32 v253, v248, v249
	global_store_dwordx4 v224, v[250:253], s[10:11]
	v_pk_fma_f32 v[242:243], v[234:235], v[208:209], v[0:1]
	v_pk_fma_f32 v[244:245], v[236:237], v[210:211], v[2:3]
	v_pk_fma_f32 v[246:247], v[238:239], v[212:213], v[4:5]
	v_pk_fma_f32 v[248:249], v[240:241], v[214:215], v[6:7]
	v_cvt_pk_bf16_f32 v250, v242, v243
	v_cvt_pk_bf16_f32 v251, v244, v245
	v_cvt_pk_bf16_f32 v252, v246, v247
	v_cvt_pk_bf16_f32 v253, v248, v249
	global_store_dwordx4 v224, v[250:253], s[46:47]
	v_pk_fma_f32 v[242:243], v[234:235], v[216:217], v[0:1]
	v_pk_fma_f32 v[244:245], v[236:237], v[218:219], v[2:3]
	v_pk_fma_f32 v[246:247], v[238:239], v[220:221], v[4:5]
	v_pk_fma_f32 v[248:249], v[240:241], v[222:223], v[6:7]
	v_cvt_pk_bf16_f32 v250, v242, v243
	v_cvt_pk_bf16_f32 v251, v244, v245
	v_cvt_pk_bf16_f32 v252, v246, v247
	v_cvt_pk_bf16_f32 v253, v248, v249
	global_store_dwordx4 v224, v[250:253], s[26:27]
	v_add_u32_e32 v224, 0x800, v224
	s_waitcnt vmcnt(8)
; __device__ __forceinline__ void phase_rwkv_mix(const Params& p) {
;     ...
;     const float4 xc = *(const float4*)(x + tok * 1024 + c);
;     float4 xp = make_float4(0.f, 0.f, 0.f, 0.f);
;     if ((tok & 4095) != 0) xp = *(const float4*)(x + (tok - 1) * 1024 + c);
;     const float dx = xp.x - xc.x, dy = xp.y - xc.y, dz = xp.z - xc.z, dw = xp.w - xc.w;
;     const float4 m0 = *(const float4*)(mu + 0 * 1024 + c), m2 = *(const float4*)(mu + 2 * 1024 + c);
;     const float4 m3 = *(const float4*)(mu + 3 * 1024 + c), m5 = *(const float4*)(mu + 5 * 1024 + c);
;     u32x2 o;
;     o.x = pack2(xc.x + dx * m0.x, xc.y + dy * m0.y); o.y = pack2(xc.z + dz * m0.z, xc.w + dw * m0.w);
;     *(u32x2*)(Ar + tok * 1024 + c) = o;
;     o.x = pack2(xc.x + dx * m2.x, xc.y + dy * m2.y); o.y = pack2(xc.z + dz * m2.z, xc.w + dw * m2.w);
;     *(u32x2*)(Ak + tok * 1024 + c) = o;
;     o.x = pack2(xc.x + dx * m3.x, xc.y + dy * m3.y); o.y = pack2(xc.z + dz * m3.z, xc.w + dw * m3.w);
;     *(u32x2*)(Av + tok * 1024 + c) = o;
;     o.x = pack2(xc.x + dx * m5.x, xc.y + dy * m5.y); o.y = pack2(xc.z + dz * m5.z, xc.w + dw * m5.w);
;     *(u32x2*)(Ag + tok * 1024 + c) = o;
	v_pk_add_f32 v[234:235], v[0:1], v[8:9] neg_lo:[0,1] neg_hi:[0,1]
	v_pk_add_f32 v[236:237], v[2:3], v[10:11] neg_lo:[0,1] neg_hi:[0,1]
	v_pk_add_f32 v[238:239], v[4:5], v[12:13] neg_lo:[0,1] neg_hi:[0,1]
	v_pk_add_f32 v[240:241], v[6:7], v[14:15] neg_lo:[0,1] neg_hi:[0,1]
	v_pk_fma_f32 v[242:243], v[234:235], v[188:189], v[8:9]
	v_pk_fma_f32 v[244:245], v[236:237], v[190:191], v[10:11]
	v_pk_fma_f32 v[246:247], v[238:239], v[192:193], v[12:13]
	v_pk_fma_f32 v[248:249], v[240:241], v[194:195], v[14:15]
	v_cvt_pk_bf16_f32 v250, v242, v243
	v_cvt_pk_bf16_f32 v251, v244, v245
	v_cvt_pk_bf16_f32 v252, v246, v247
	v_cvt_pk_bf16_f32 v253, v248, v249
	global_store_dwordx4 v224, v[250:253], s[42:43]
	v_pk_fma_f32 v[242:243], v[234:235], v[196:197], v[8:9]
	v_pk_fma_f32 v[244:245], v[236:237], v[198:199], v[10:11]
	v_pk_fma_f32 v[246:247], v[238:239], v[200:201], v[12:13]
	v_pk_fma_f32 v[248:249], v[240:241], v[202:203], v[14:15]
	v_cvt_pk_bf16_f32 v250, v242, v243
	v_cvt_pk_bf16_f32 v251, v244, v245
	v_cvt_pk_bf16_f32 v252, v246, v247
	v_cvt_pk_bf16_f32 v253, v248, v249
	global_store_dwordx4 v224, v[250:253], s[10:11]
	v_pk_fma_f32 v[242:243], v[234:235], v[208:209], v[8:9]
	v_pk_fma_f32 v[244:245], v[236:237], v[210:211], v[10:11]
	v_pk_fma_f32 v[246:247], v[238:239], v[212:213], v[12:13]
	v_pk_fma_f32 v[248:249], v[240:241], v[214:215], v[14:15]
	v_cvt_pk_bf16_f32 v250, v242, v243
	v_cvt_pk_bf16_f32 v251, v244, v245
	v_cvt_pk_bf16_f32 v252, v246, v247
	v_cvt_pk_bf16_f32 v253, v248, v249
	global_store_dwordx4 v224, v[250:253], s[46:47]
	v_pk_fma_f32 v[242:243], v[234:235], v[216:217], v[8:9]
	v_pk_fma_f32 v[244:245], v[236:237], v[218:219], v[10:11]
	v_pk_fma_f32 v[246:247], v[238:239], v[220:221], v[12:13]
	v_pk_fma_f32 v[248:249], v[240:241], v[222:223], v[14:15]
	v_cvt_pk_bf16_f32 v250, v242, v243
	v_cvt_pk_bf16_f32 v251, v244, v245
	v_cvt_pk_bf16_f32 v252, v246, v247
	v_cvt_pk_bf16_f32 v253, v248, v249
	global_store_dwordx4 v224, v[250:253], s[26:27]
	v_add_u32_e32 v224, 0x800, v224
	s_waitcnt vmcnt(10)
	v_pk_add_f32 v[234:235], v[8:9], v[16:17] neg_lo:[0,1] neg_hi:[0,1]
	v_pk_add_f32 v[236:237], v[10:11], v[18:19] neg_lo:[0,1] neg_hi:[0,1]
	v_pk_add_f32 v[238:239], v[12:13], v[20:21] neg_lo:[0,1] neg_hi:[0,1]
	v_pk_add_f32 v[240:241], v[14:15], v[22:23] neg_lo:[0,1] neg_hi:[0,1]
	v_pk_fma_f32 v[242:243], v[234:235], v[188:189], v[16:17]
	v_pk_fma_f32 v[244:245], v[236:237], v[190:191], v[18:19]
	v_pk_fma_f32 v[246:247], v[238:239], v[192:193], v[20:21]
	v_pk_fma_f32 v[248:249], v[240:241], v[194:195], v[22:23]
	v_cvt_pk_bf16_f32 v250, v242, v243
	v_cvt_pk_bf16_f32 v251, v244, v245
	v_cvt_pk_bf16_f32 v252, v246, v247
	v_cvt_pk_bf16_f32 v253, v248, v249
	global_store_dwordx4 v224, v[250:253], s[42:43]
	v_pk_fma_f32 v[242:243], v[234:235], v[196:197], v[16:17]
	v_pk_fma_f32 v[244:245], v[236:237], v[198:199], v[18:19]
	v_pk_fma_f32 v[246:247], v[238:239], v[200:201], v[20:21]
	v_pk_fma_f32 v[248:249], v[240:241], v[202:203], v[22:23]
	v_cvt_pk_bf16_f32 v250, v242, v243
	v_cvt_pk_bf16_f32 v251, v244, v245
	v_cvt_pk_bf16_f32 v252, v246, v247
	v_cvt_pk_bf16_f32 v253, v248, v249
	global_store_dwordx4 v224, v[250:253], s[10:11]
	v_pk_fma_f32 v[242:243], v[234:235], v[208:209], v[16:17]
	v_pk_fma_f32 v[244:245], v[236:237], v[210:211], v[18:19]
	v_pk_fma_f32 v[246:247], v[238:239], v[212:213], v[20:21]
	v_pk_fma_f32 v[248:249], v[240:241], v[214:215], v[22:23]
	v_cvt_pk_bf16_f32 v250, v242, v243
	v_cvt_pk_bf16_f32 v251, v244, v245
	v_cvt_pk_bf16_f32 v252, v246, v247
	v_cvt_pk_bf16_f32 v253, v248, v249
	global_store_dwordx4 v224, v[250:253], s[46:47]
	v_pk_fma_f32 v[242:243], v[234:235], v[216:217], v[16:17]
	v_pk_fma_f32 v[244:245], v[236:237], v[218:219], v[18:19]
	v_pk_fma_f32 v[246:247], v[238:239], v[220:221], v[20:21]
	v_pk_fma_f32 v[248:249], v[240:241], v[222:223], v[22:23]
	v_cvt_pk_bf16_f32 v250, v242, v243
	v_cvt_pk_bf16_f32 v251, v244, v245
	v_cvt_pk_bf16_f32 v252, v246, v247
	v_cvt_pk_bf16_f32 v253, v248, v249
	global_store_dwordx4 v224, v[250:253], s[26:27]
	v_add_u32_e32 v224, 0x800, v224
	s_waitcnt vmcnt(12)
	v_pk_add_f32 v[234:235], v[16:17], v[24:25] neg_lo:[0,1] neg_hi:[0,1]
	v_pk_add_f32 v[236:237], v[18:19], v[26:27] neg_lo:[0,1] neg_hi:[0,1]
	v_pk_add_f32 v[238:239], v[20:21], v[28:29] neg_lo:[0,1] neg_hi:[0,1]
	v_pk_add_f32 v[240:241], v[22:23], v[30:31] neg_lo:[0,1] neg_hi:[0,1]
	v_pk_fma_f32 v[242:243], v[234:235], v[188:189], v[24:25]
	v_pk_fma_f32 v[244:245], v[236:237], v[190:191], v[26:27]
	v_pk_fma_f32 v[246:247], v[238:239], v[192:193], v[28:29]
	v_pk_fma_f32 v[248:249], v[240:241], v[194:195], v[30:31]
	v_cvt_pk_bf16_f32 v250, v242, v243
	v_cvt_pk_bf16_f32 v251, v244, v245
	v_cvt_pk_bf16_f32 v252, v246, v247
	v_cvt_pk_bf16_f32 v253, v248, v249
	global_store_dwordx4 v224, v[250:253], s[42:43]
	v_pk_fma_f32 v[242:243], v[234:235], v[196:197], v[24:25]
	v_pk_fma_f32 v[244:245], v[236:237], v[198:199], v[26:27]
	v_pk_fma_f32 v[246:247], v[238:239], v[200:201], v[28:29]
	v_pk_fma_f32 v[248:249], v[240:241], v[202:203], v[30:31]
	v_cvt_pk_bf16_f32 v250, v242, v243
	v_cvt_pk_bf16_f32 v251, v244, v245
	v_cvt_pk_bf16_f32 v252, v246, v247
	v_cvt_pk_bf16_f32 v253, v248, v249
	global_store_dwordx4 v224, v[250:253], s[10:11]
	v_pk_fma_f32 v[242:243], v[234:235], v[208:209], v[24:25]
	v_pk_fma_f32 v[244:245], v[236:237], v[210:211], v[26:27]
	v_pk_fma_f32 v[246:247], v[238:239], v[212:213], v[28:29]
	v_pk_fma_f32 v[248:249], v[240:241], v[214:215], v[30:31]
	v_cvt_pk_bf16_f32 v250, v242, v243
	v_cvt_pk_bf16_f32 v251, v244, v245
	v_cvt_pk_bf16_f32 v252, v246, v247
	v_cvt_pk_bf16_f32 v253, v248, v249
	global_store_dwordx4 v224, v[250:253], s[46:47]
	v_pk_fma_f32 v[242:243], v[234:235], v[216:217], v[24:25]
	v_pk_fma_f32 v[244:245], v[236:237], v[218:219], v[26:27]
	v_pk_fma_f32 v[246:247], v[238:239], v[220:221], v[28:29]
	v_pk_fma_f32 v[248:249], v[240:241], v[222:223], v[30:31]
	v_cvt_pk_bf16_f32 v250, v242, v243
	v_cvt_pk_bf16_f32 v251, v244, v245
	v_cvt_pk_bf16_f32 v252, v246, v247
	v_cvt_pk_bf16_f32 v253, v248, v249
	global_store_dwordx4 v224, v[250:253], s[26:27]
	v_add_u32_e32 v224, 0x800, v224
	v_mov_b32_e32 v226, v24
	v_mov_b32_e32 v227, v25
	v_mov_b32_e32 v228, v26
	v_mov_b32_e32 v229, v27
	v_mov_b32_e32 v230, v28
	v_mov_b32_e32 v231, v29
	v_mov_b32_e32 v232, v30
	v_mov_b32_e32 v233, v31
	s_cmp_lg_u32 s20, 0
	s_cbranch_scc1 .Lmy_mix_loop
	s_branch .LBB0_466
